# phases I and J (layers 0-2): the workgroups with one tile of slack (128..255) start about half a tile late (3 x s_sleep 127), de-phasing their DMA / store bursts from the other half's at no cost to th
# speedup vs baseline: 1.0003x; 1.0003x over previous
; #define LAS __attribute__((address_space(3)))
;     __device__ __forceinline__ long bhalf(const Unit&) const { return (long)HALF * ldb * 2; }
; template <bool HM = false, bool PERM = false, bool CP = false, class Prob, class Epi>
; __device__ __forceinline__ void gemm_phase(LAS unsigned char* lds, const Prob& S, const Epi& E) {
;     int tid = threadIdx.x; asm volatile("" : "+v"(tid));
;     const int wid = __builtin_amdgcn_readfirstlane(tid >> 6), lane = tid & 63, wr = wid >> 2, wc = wid & 3, fr = lane & 15, fq = lane >> 4;
;     unsigned voffA[2], voffB[2];
; #pragma unroll
;     for (int i = 0; i < 2; ++i) { int R, C; stage_rc(tid * 16 + i * 8192, R, C); const int Rb = PERM ? ((R & ~31) + perm32(R & 31)) : R; voffA[i] = (unsigned)(R * S.lda + C) * 2u; voffB[i] = (unsigned)(Rb * S.ldb + C) * 2u; }
;     const size_t kstepA = S.kstepA(), kstepB = S.kstepB();
;     const size_t hstepA = HM ? 0 : (size_t)HALF * S.lda * 2; const long hstepB0 = (long)HALF * S.ldb * 2;
;     const unsigned ldsw = (unsigned)wid * 1024u;
;     const int aoff = lds_byte(wr * 64 + fr, fq * 8), boff = lds_byte(wc * 32 + fr, fq * 8);
;     ...
;     Unit cur, nxt; int ui = 0;
;     if (!S.next(0, cur)) return;
;     f32x4 acc[2][2][4][2];
; #pragma unroll
;     for (int a = 0; a < 2; ++a)
; #pragma unroll
;         for (int b = 0; b < 2; ++b)
; #pragma unroll
;             for (int m = 0; m < 4; ++m)
; #pragma unroll
;                 for (int n = 0; n < 2; ++n) acc[a][b][m][n] = (f32x4){0.f, 0.f, 0.f, 0.f};
;     bf16x8 At[4][2], B0[2][2], B1[2][2];
;     const char* cA = S.abase(cur);
;     const char* cB = S.bbase(cur);
;     long chB = CP ? S.bhalf(cur) : hstepB0; bool fullu = CP ? S.full(cur) : true;
;     ...
;     PG8_STAGE(PG8_SB(0, 0), cB, voffB); PG8_STAGE(PG8_SB(0, 1), cB + chB, voffB); PG8_STAGE(PG8_SA(0, 0), cA, voffA); PG8_STAGE(PG8_SA(0, 1), cA + hstepA, voffA);
;     if (wr == 1) PG8_BAR;
;     PG8_WAIT_V(2); PG8_BAR;
;     PG8_STAGE(PG8_SB(1, 0), cB + kstepB, voffB); PG8_STAGE(PG8_SA(1, 0), cA + kstepA, voffA); PG8_STAGE(PG8_SB(1, 1), cB + chB + kstepB, voffB);
; __global__ __launch_bounds__(512, 2) void mega(Args a_) {
;     ...
;         PH_BEGIN {
;             { pg8::StdProb P(WSP(OFF_HN), WSP(OFF_WB), DM, DM, DM, 0, 0, l == DEPTH - 1 ? 128 : 136, 16, 1, G, c); P.skipctx = l == DEPTH - 1;
;               pg8::gemm_phase<false, true>(lds, P, EpiSqReluP{WSP(OFF_R1)}); }
.LBB0_1214:
	s_andn2_b64 vcc, exec, s[0:1]
	s_cbranch_vccnz .LBB0_1323
	v_readlane_b32 s8, v237, 2
	v_readlane_b32 s9, v237, 3
	s_cmp_gt_u32 s46, 2
	s_cbranch_scc1 .Li_nodelay
	s_cmpk_lt_i32 s84, 0x80
	s_cbranch_scc1 .Li_nodelay
	s_load_dword s100, s[8:9], 0xf0
	s_waitcnt lgkmcnt(0)
	s_cmpk_lg_i32 s100, 0x100
	s_cbranch_scc1 .Li_nodelay
	s_sleep 127
	s_sleep 127
	s_sleep 127
.Li_nodelay:
	s_mov_b64 s[4:5], s[8:9]
	s_mov_b32 s2, s46
	s_load_dwordx2 s[0:1], s[8:9], 0xf0
	s_cmp_eq_u32 s2, 3
	s_mov_b32 s3, s84
	s_cselect_b64 s[16:17], -1, 0
	v_mov_b32_e32 v15, v216
	s_waitcnt lgkmcnt(0)
	s_mov_b32 s18, s0
	s_load_dwordx2 s[14:15], s[4:5], 0xe0
	s_and_b64 s[0:1], s[16:17], exec
	s_movk_i32 s0, 0x88
	s_cselect_b32 s19, 0x80, s0
	s_lshl_b32 s31, s19, 4
	s_cmp_ge_i32 s3, s31
	v_readfirstlane_b32 s34, v15
	s_cbranch_scc1 .LBB0_1231
	v_lshlrev_b32_e32 v2, 4, v15
	v_add_u32_e32 v3, 0x2000, v2
	v_ashrrev_i32_e32 v0, 31, v3
	v_lshrrev_b32_e32 v0, 22, v0
	v_add_u32_e32 v0, v3, v0
	v_ashrrev_i32_e32 v0, 10, v0
	v_mul_i32_i24_e32 v4, 0x400, v0
	v_sub_u32_e32 v3, v3, v4
	v_lshrrev_b32_e32 v4, 4, v3
	v_bitop3_b32 v3, v4, v3, 32 bitop3:0x6c
	v_ashrrev_i32_e32 v4, 31, v3
	v_lshrrev_b32_e32 v4, 26, v4
	v_add_u32_e32 v4, v3, v4
	v_lshlrev_b32_e32 v5, 3, v0
	v_ashrrev_i32_e32 v10, 6, v4
	v_and_b32_e32 v5, -16, v5
	v_add_u32_e32 v5, v10, v5
	v_and_b32_e32 v6, 3, v10
	s_mov_b32 s0, 0x1fffe0
	v_lshrrev_b32_e32 v7, 2, v5
	v_lshlrev_b32_e32 v8, 1, v5
	v_and_b32_e32 v4, 0xc0, v4
	v_and_or_b32 v6, v5, s0, v6
	v_and_b32_e32 v7, 4, v7
	v_and_b32_e32 v8, 24, v8
	v_sub_u32_e32 v3, v3, v4
	v_or3_b32 v6, v6, v7, v8
	v_lshlrev_b32_e32 v7, 5, v0
	v_ashrrev_i16_sdwa v3, v220, sext(v3) dst_sel:DWORD dst_unused:UNUSED_PAD src0_sel:DWORD src1_sel:BYTE_0
	v_and_b32_e32 v7, 32, v7
	v_bfe_i32 v11, v3, 0, 16
	v_add_lshl_u32 v3, v7, v11, 1
	v_lshl_add_u32 v130, v6, 11, v3
	v_lshl_add_u32 v132, v5, 11, v3
	v_bfe_i32 v3, v15, 27, 1
	v_lshrrev_b32_e32 v3, 22, v3
	v_add_u32_e32 v3, v2, v3
	v_and_b32_e32 v3, 0xfffffc00, v3
	v_sub_u32_e32 v2, v2, v3
	v_lshrrev_b32_e32 v3, 4, v2
	v_ashrrev_i32_e32 v4, 31, v15
	v_bitop3_b32 v2, v3, v2, 32 bitop3:0x6c
	v_lshrrev_b32_e32 v4, 26, v4
	v_ashrrev_i32_e32 v3, 31, v2
	v_add_u32_e32 v4, v15, v4
	v_lshrrev_b32_e32 v3, 26, v3
	v_ashrrev_i32_e32 v13, 6, v4
	v_add_u32_e32 v3, v2, v3
	v_lshlrev_b32_e32 v4, 3, v13
	v_ashrrev_i32_e32 v12, 6, v3
	v_and_b32_e32 v4, -16, v4
	v_add_u32_e32 v4, v12, v4
	v_and_b32_e32 v5, 3, v12
	v_lshrrev_b32_e32 v6, 2, v4
	v_lshlrev_b32_e32 v7, 1, v4
	v_and_or_b32 v5, v4, s0, v5
	v_and_b32_e32 v6, 4, v6
	v_and_b32_e32 v7, 24, v7
	v_or3_b32 v5, v5, v6, v7
	v_cvt_f32_u32_e32 v7, s31
	v_and_b32_e32 v3, 0xc0, v3
	v_sub_u32_e32 v2, v2, v3
	v_ashrrev_i16_sdwa v2, v220, sext(v2) dst_sel:DWORD dst_unused:UNUSED_PAD src0_sel:DWORD src1_sel:BYTE_0
	v_bfe_i32 v14, v2, 0, 16
	v_rcp_iflag_f32_e32 v2, v7
	s_waitcnt lgkmcnt(0)
	s_add_u32 s33, s14, 0x33f8000
	s_addc_u32 s52, s15, 0
	s_add_u32 s53, s14, 0x23f8000
	v_mul_f32_e32 v2, 0x4f7ffffe, v2
	v_cvt_u32_f32_e32 v2, v2
	s_addc_u32 s54, s15, 0
	s_sub_i32 s6, 0, s31
	s_abs_i32 s1, s3
	v_readfirstlane_b32 s56, v2
	s_mul_i32 s6, s6, s56
	s_mul_hi_u32 s6, s56, s6
	s_add_i32 s56, s56, s6
	s_mul_hi_u32 s6, s1, s56
	s_mul_i32 s6, s6, s31
	s_ashr_i32 s35, s34, 6
	s_sub_i32 s1, s1, s6
	s_ashr_i32 s38, s34, 8
	s_lshl_b32 s55, s35, 10
	s_ashr_i32 s0, s3, 31
	s_sub_i32 s6, s1, s31
	s_cmp_ge_u32 s1, s31
	s_cselect_b32 s1, s6, s1
	s_sub_i32 s6, s1, s31
	s_cmp_ge_u32 s1, s31
	s_cselect_b32 s1, s6, s1
	s_xor_b32 s1, s1, s0
	s_sub_i32 s0, s1, s0
	s_sext_i32_i16 s1, s0
	s_bfe_u32 s1, s1, 0x3001c
	s_add_i32 s1, s0, s1
	s_and_b32 s6, s1, 0xfff8
	s_sub_i32 s0, s0, s6
	s_lshl_b32 s58, s19, 1
	s_bfe_u32 s6, s0, 0x1000f
	s_or_b32 s6, s58, s6
	s_sext_i32_i16 s1, s1
	s_mul_i32 s0, s6, s0
	s_ashr_i32 s1, s1, 3
	s_add_i32 s0, s0, s1
	s_sext_i32_i16 s1, s0
	s_bfe_u32 s1, s1, 0x70018
	s_add_i32 s1, s0, s1
	s_sext_i32_i16 s6, s1
	s_ashr_i32 s6, s6, 7
	s_lshl_b32 s8, s6, 3
	s_sub_i32 s6, s19, s8
	s_min_i32 s9, s6, 8
	s_sext_i32_i8 s6, s9
	v_cvt_f32_i32_e32 v2, s6
	v_lshlrev_b32_e32 v6, 5, v13
	s_and_b32 s1, s1, 0xff80
	v_and_b32_e32 v6, 32, v6
	s_sub_i32 s0, s0, s1
	v_add_lshl_u32 v3, v6, v14, 1
	s_sext_i32_i16 s22, s0
	v_lshl_add_u32 v134, v5, 11, v3
	v_lshl_add_u32 v136, v4, 11, v3
	v_cvt_f32_i32_e32 v3, s22
	v_rcp_iflag_f32_e32 v4, v2
	s_xor_b32 s0, s22, s6
	s_ashr_i32 s0, s0, 30
	s_or_b32 s6, s0, 1
	v_mul_f32_e32 v4, v3, v4
	v_trunc_f32_e32 v4, v4
	v_fma_f32 v3, -v4, v2, v3
	v_cvt_i32_f32_e32 v4, v4
	v_cmp_ge_f32_e64 s[0:1], |v3|, |v2|
	s_and_b64 s[0:1], s[0:1], exec
	s_cselect_b32 s0, s6, 0
	v_readfirstlane_b32 s1, v4
	s_add_i32 s6, s1, s0
	s_mul_i32 s0, s6, s9
	s_sub_i32 s0, s22, s0
	s_sext_i32_i8 s0, s0
	s_add_i32 s8, s8, s0
	s_ashr_i32 s0, s8, 4
	s_add_i32 s0, s8, s0
	s_add_i32 s9, s0, 1
	s_and_b64 s[0:1], s[16:17], exec
	s_cselect_b32 s8, s9, s8
	s_bfe_i64 s[0:1], s[6:7], 0x80000
	s_ashr_i32 s9, s8, 31
	s_lshl_b64 s[0:1], s[0:1], 19
	s_add_u32 s24, s53, s0
	s_addc_u32 s25, s54, s1
	s_add_i32 s59, s55, 0
	s_add_i32 m0, s59, 0x10000
	v_mov_b32_e32 v135, v1
	global_load_lds_dwordx4 v134, s[24:25]
	s_add_i32 m0, s59, 0x12000
	s_add_u32 s0, s24, 0x40000
	global_load_lds_dwordx4 v130, s[24:25]
	s_addc_u32 s1, s25, 0
	s_add_i32 m0, s59, 0x14000
	v_mov_b32_e32 v131, v1
	global_load_lds_dwordx4 v134, s[0:1]
	s_add_i32 m0, s59, 0x16000
	v_mov_b32_e32 v137, v1
	global_load_lds_dwordx4 v130, s[0:1]
	s_lshl_b64 s[0:1], s[8:9], 19
	s_add_u32 s0, s33, s0
	s_addc_u32 s1, s52, s1
	s_add_i32 s9, s59, 0x2000
	s_mov_b32 m0, s59
	s_add_u32 s22, s0, 0x40000
	global_load_lds_dwordx4 v136, s[0:1]
	s_mov_b32 m0, s9
	s_addc_u32 s23, s1, 0
	s_add_i32 s60, s59, 0x4000
	global_load_lds_dwordx4 v132, s[0:1]
	s_mov_b32 m0, s60
	s_add_i32 s61, s59, 0x6000
	global_load_lds_dwordx4 v136, s[22:23]
	s_mov_b32 m0, s61
	v_mov_b32_e32 v133, v1
	global_load_lds_dwordx4 v132, s[22:23]
	s_cmp_eq_u32 s38, 1
	v_lshl_add_u64 v[8:9], s[24:25], 0, v[134:135]
	v_lshl_add_u64 v[6:7], s[24:25], 0, v[130:131]
	v_lshl_add_u64 v[2:3], s[0:1], 0, v[136:137]
	s_cselect_b64 s[22:23], -1, 0
	s_cmp_lg_u32 s38, 1
	v_lshl_add_u64 v[4:5], s[0:1], 0, v[132:133]
	s_cbranch_scc1 .LBB0_1218
	s_barrier

; #define PH_BEGIN if (ph >= ph_lo && ph < ph_hi) { KArgs* ap_ = (KArgs*)__builtin_amdgcn_kernarg_segment_ptr(); asm volatile("" : "+s"(ap_)); KArgs& a = *ap_; \
;         int l = lv; asm volatile("" : "+s"(l)); int G = gridDim.x, c = blockIdx.x; asm volatile("" : "+s"(G), "+s"(c)); unsigned char* ws = a.ws; (void)l; (void)G; (void)c; (void)ws;
;     __device__ __forceinline__ bool next(int i, Unit& u) const {
;         const int L = i * G + c; const int ntail = nunits - nfull;
;         if (L < nfull) { u.batch = 0; u.aux = 0; std_map(L, 136, 4, u.pm, u.pn); return true; }
;         const int j = L - nfull; if (j >= ntail * NS) return false;
;         u.batch = 1 + j / ntail; u.aux = j % ntail; std_map(nfull + u.aux, 136, 4, u.pm, u.pn); return true;
;     }
; __global__ __launch_bounds__(512, 2) void mega(Args a_) {
;     ...
;         PH_BEGIN {
;             const EpiResid E{(float*)(ws + OFF_XC), a.out, (const float*)(ws + OFF_MODS) + (size_t)l * 9 * 6144, 5, (float*)(ws + OFF_A2)};
;             if (l == DEPTH - 1) { pg8::StdProb P(WSP(OFF_R1), WSP(OFF_WB) + (size_t)HID * DM, 64, 64, HID, 0, 0, 128, 4, 1, G, c); P.skipctx = true; P.ksA = (size_t)MTOK * 128; P.ksB = (size_t)DM * 128; pg8::gemm_phase(lds, P, E); }
;             else { pg8::TailProb<4> P(WSP(OFF_R1), WSP(OFF_WB) + (size_t)HID * DM, 64, HID, G, c, G == 256); P.ksA = (size_t)MTOK * 128; P.ksB = (size_t)DM * 128; P.sliceA = (size_t)16 * MTOK * 64; P.sliceB = (size_t)16 * DM * 64;
;                    pg8::gemm_phase(lds, P, E); }
.LBB0_1326:
	v_readlane_b32 s8, v237, 2
	v_readlane_b32 s9, v237, 3
	s_cmp_gt_u32 s46, 2
	s_cbranch_scc1 .Lj_nodelay
	s_cmpk_lt_i32 s84, 0x80
	s_cbranch_scc1 .Lj_nodelay
	s_load_dword s100, s[8:9], 0xf0
	s_waitcnt lgkmcnt(0)
	s_cmpk_lg_i32 s100, 0x100
	s_cbranch_scc1 .Lj_nodelay
	s_sleep 127
	s_sleep 127
	s_sleep 127
.Lj_nodelay:
	s_mov_b64 s[0:1], s[8:9]
	s_mov_b32 s2, s46
	s_load_dwordx2 s[4:5], s[8:9], 0xf0
	s_mov_b32 s61, s84
	s_waitcnt lgkmcnt(0)
	s_mov_b32 s60, s4
	s_load_dwordx4 s[52:55], s[0:1], 0xd8
	s_mul_i32 s1, s2, 0x36000
	s_mul_hi_i32 s0, s2, 0x36000
	s_waitcnt lgkmcnt(0)
	s_add_u32 s1, s54, s1
	s_addc_u32 s0, s55, s0
	s_add_u32 s62, s1, 0x800000
	s_addc_u32 s63, s0, 0
	s_add_u32 s42, s54, 0x77f8000
	s_addc_u32 s43, s55, 0
	s_add_u32 s65, s54, 0xcaf8000
	s_addc_u32 s66, s55, 0
	s_add_u32 s67, s54, 0x2bf8000
	s_addc_u32 s68, s55, 0
	s_cmp_lg_u32 s2, 3
	s_mov_b64 s[0:1], -1
	s_cbranch_scc0 .LBB0_1374
	s_cmpk_eq_i32 s60, 0x100
	s_movk_i32 s0, 0x200
	s_cselect_b32 s6, s0, 0x220
	v_mov_b32_e32 v2, v216
	s_xor_b32 s69, s6, 0x220
	s_cmp_lt_i32 s61, s6
	v_readfirstlane_b32 s2, v2
	s_cbranch_scc1 .LBB0_1332
	s_sub_i32 s4, s61, s6
	s_lshl_b32 s0, s69, 2
	s_cmp_lt_i32 s4, s0
	s_mov_b64 s[0:1], 0
	s_cbranch_scc0 .LBB0_1330
	s_sext_i32_i8 s0, s69
	v_cvt_f32_i32_e32 v0, s0
	s_sext_i32_i8 s1, s4
	v_cvt_f32_i32_e32 v3, s1
	s_xor_b32 s0, s1, s0
	v_rcp_iflag_f32_e32 v4, v0
	s_ashr_i32 s0, s0, 30
	s_or_b32 s3, s0, 1
	v_mul_f32_e32 v4, v3, v4
	v_trunc_f32_e32 v4, v4
	v_fma_f32 v3, -v4, v0, v3
	v_cvt_i32_f32_e32 v4, v4
	v_cmp_ge_f32_e64 s[0:1], |v3|, |v0|
	s_and_b64 s[0:1], s[0:1], exec
	s_cselect_b32 s0, s3, 0
	v_readfirstlane_b32 s1, v4
	s_add_i32 s0, s1, s0
	s_sext_i32_i8 s1, s0
	s_mul_i32 s0, s0, s69
	s_sub_i32 s0, s4, s0
	s_sext_i32_i8 s78, s0
	s_add_i32 s64, s1, 1
	s_add_i32 s3, s6, s78
	s_mov_b64 s[0:1], -1
